# FF1 tile transitions: closing and opening waits only cover the next tile's first-k-tile LDS-DMA loads (vmcnt(16)), not the 16 epilogue stores
# baseline (speedup 1.0000x reference)
.LBB0_1651:
	s_or_b64 exec, exec, s[60:61]
	v_and_b32_e32 v134, 64, v165
	v_xor_b32_e32 v132, 16, v165
	v_add_u32_e32 v134, 64, v134
	v_max_f32_e32 v124, v124, v124
	v_max_f32_e32 v125, v125, v125
	v_and_b32_e32 v128, 16, v128
	v_lshlrev_b32_e32 v133, 2, v155
	v_cmp_lt_i32_e32 vcc, v132, v134
	v_max_f32_e32 v124, 0, v124
	v_max_f32_e32 v125, 0, v125
	v_max_f32_e32 v126, v126, v126
	v_max_f32_e32 v127, v127, v127
	v_max_f32_e32 v120, v120, v120
	v_max_f32_e32 v121, v121, v121
	v_cndmask_b32_e32 v132, v165, v132, vcc
	v_add_u32_e32 v134, 12, v133
	v_cmp_eq_u32_e32 vcc, 0, v128
	v_max_f32_e32 v126, 0, v126
	v_max_f32_e32 v127, 0, v127
	v_pk_mul_f32 v[124:125], v[124:125], v[124:125]
	v_max_f32_e32 v120, 0, v120
	v_max_f32_e32 v121, 0, v121
	v_max_f32_e32 v122, v122, v122
	v_max_f32_e32 v123, v123, v123
	v_cndmask_b32_e32 v128, v134, v133, vcc
	v_cvt_pk_bf16_f32 v133, v124, v125
	v_pk_mul_f32 v[124:125], v[126:127], v[126:127]
	v_max_f32_e32 v122, 0, v122
	v_max_f32_e32 v123, 0, v123
	v_pk_mul_f32 v[120:121], v[120:121], v[120:121]
	v_cvt_pk_bf16_f32 v126, v124, v125
	v_cvt_pk_bf16_f32 v124, v120, v121
	v_pk_mul_f32 v[120:121], v[122:123], v[122:123]
	v_lshlrev_b32_e32 v132, 2, v132
	v_cvt_pk_bf16_f32 v122, v120, v121
	v_cndmask_b32_e32 v120, v126, v122, vcc
	v_cndmask_b32_e32 v121, v133, v124, vcc
	ds_bpermute_b32 v123, v132, v120
	ds_bpermute_b32 v127, v132, v121
	s_lshl_b32 s1, s71, 8
	v_or_b32_e32 v130, s36, v156
	v_lshlrev_b32_e32 v131, 5, v154
	v_max_f32_e32 v116, v116, v116
	v_max_f32_e32 v117, v117, v117
	v_max_f32_e32 v112, v112, v112
	v_max_f32_e32 v113, v113, v113
	v_add_u32_e32 v130, v130, v157
	v_or3_b32 v120, v131, s1, v128
	v_max_f32_e32 v116, 0, v116
	v_max_f32_e32 v117, 0, v117
	v_max_f32_e32 v118, v118, v118
	v_max_f32_e32 v119, v119, v119
	v_max_f32_e32 v112, 0, v112
	v_max_f32_e32 v113, 0, v113
	v_max_f32_e32 v114, v114, v114
	v_max_f32_e32 v115, v115, v115
	v_lshlrev_b32_e32 v128, 1, v120
	v_ashrrev_i32_e32 v131, 31, v130
	v_max_f32_e32 v118, 0, v118
	v_max_f32_e32 v119, 0, v119
	v_pk_mul_f32 v[116:117], v[116:117], v[116:117]
	v_max_f32_e32 v114, 0, v114
	v_max_f32_e32 v115, 0, v115
	v_pk_mul_f32 v[112:113], v[112:113], v[112:113]
	v_max_f32_e32 v108, v108, v108
	v_max_f32_e32 v109, v109, v109
	v_max_f32_e32 v104, v104, v104
	v_max_f32_e32 v105, v105, v105
	v_lshl_add_u64 v[120:121], s[4:5], 0, v[128:129]
	s_waitcnt lgkmcnt(0)
	v_cndmask_b32_e32 v125, v122, v123, vcc
	v_cndmask_b32_e32 v124, v124, v127, vcc
	v_cndmask_b32_e32 v123, v123, v126, vcc
	v_cndmask_b32_e32 v122, v127, v133, vcc
	v_lshlrev_b64 v[126:127], 13, v[130:131]
	v_cvt_pk_bf16_f32 v128, v116, v117
	v_pk_mul_f32 v[116:117], v[118:119], v[118:119]
	v_cvt_pk_bf16_f32 v131, v112, v113
	v_pk_mul_f32 v[112:113], v[114:115], v[114:115]
	v_max_f32_e32 v108, 0, v108
	v_max_f32_e32 v109, 0, v109
	v_max_f32_e32 v110, v110, v110
	v_max_f32_e32 v111, v111, v111
	v_max_f32_e32 v104, 0, v104
	v_max_f32_e32 v105, 0, v105
	v_max_f32_e32 v106, v106, v106
	v_max_f32_e32 v107, v107, v107
	v_cvt_pk_bf16_f32 v119, v116, v117
	v_cvt_pk_bf16_f32 v112, v112, v113
	v_lshl_add_u64 v[116:117], v[120:121], 0, v[126:127]
	v_max_f32_e32 v110, 0, v110
	v_max_f32_e32 v111, 0, v111
	v_pk_mul_f32 v[108:109], v[108:109], v[108:109]
	v_max_f32_e32 v106, 0, v106
	v_max_f32_e32 v107, 0, v107
	v_pk_mul_f32 v[104:105], v[104:105], v[104:105]
	v_cndmask_b32_e32 v113, v119, v112, vcc
	global_store_dwordx4 v[116:117], v[122:125], off
	ds_bpermute_b32 v113, v132, v113
	v_cndmask_b32_e32 v114, v128, v131, vcc
	v_cvt_pk_bf16_f32 v122, v108, v109
	v_pk_mul_f32 v[108:109], v[110:111], v[110:111]
	v_cvt_pk_bf16_f32 v123, v104, v105
	v_pk_mul_f32 v[104:105], v[106:107], v[106:107]
	v_cvt_pk_bf16_f32 v111, v108, v109
	v_cvt_pk_bf16_f32 v104, v104, v105
	v_cndmask_b32_e32 v105, v111, v104, vcc
	ds_bpermute_b32 v133, v132, v114
	ds_bpermute_b32 v105, v132, v105
	v_cndmask_b32_e32 v106, v122, v123, vcc
	v_or_b32_e32 v118, 16, v130
	ds_bpermute_b32 v124, v132, v106
	s_waitcnt lgkmcnt(0)
	v_cndmask_b32_e32 v115, v112, v113, vcc
	v_cndmask_b32_e32 v113, v113, v119, vcc
	v_ashrrev_i32_e32 v119, 31, v118
	v_max_f32_e32 v100, v100, v100
	v_max_f32_e32 v101, v101, v101
	v_max_f32_e32 v96, v96, v96
	v_max_f32_e32 v97, v97, v97
	v_lshlrev_b64 v[118:119], 13, v[118:119]
	v_or_b32_e32 v110, 32, v130
	v_max_f32_e32 v100, 0, v100
	v_max_f32_e32 v101, 0, v101
	v_max_f32_e32 v102, v102, v102
	v_max_f32_e32 v103, v103, v103
	v_max_f32_e32 v96, 0, v96
	v_max_f32_e32 v97, 0, v97
	v_max_f32_e32 v98, v98, v98
	v_max_f32_e32 v99, v99, v99
	v_cndmask_b32_e32 v114, v131, v133, vcc
	v_cndmask_b32_e32 v112, v133, v128, vcc
	v_lshl_add_u64 v[108:109], v[120:121], 0, v[118:119]
	v_cndmask_b32_e32 v107, v104, v105, vcc
	v_cndmask_b32_e32 v105, v105, v111, vcc
	v_ashrrev_i32_e32 v111, 31, v110
	v_max_f32_e32 v102, 0, v102
	v_max_f32_e32 v103, 0, v103
	v_pk_mul_f32 v[100:101], v[100:101], v[100:101]
	v_max_f32_e32 v98, 0, v98
	v_max_f32_e32 v99, 0, v99
	v_pk_mul_f32 v[96:97], v[96:97], v[96:97]
	v_max_f32_e32 v92, v92, v92
	v_max_f32_e32 v93, v93, v93
	global_store_dwordx4 v[108:109], v[112:115], off
	v_lshlrev_b64 v[110:111], 13, v[110:111]
	v_max_f32_e32 v92, 0, v92
	v_cvt_pk_bf16_f32 v112, v100, v101
	v_pk_mul_f32 v[100:101], v[102:103], v[102:103]
	v_cvt_pk_bf16_f32 v113, v96, v97
	v_pk_mul_f32 v[96:97], v[98:99], v[98:99]
	v_max_f32_e32 v93, 0, v93
	v_max_f32_e32 v94, v94, v94
	v_max_f32_e32 v95, v95, v95
	v_max_f32_e32 v88, v88, v88
	v_max_f32_e32 v89, v89, v89
	v_cndmask_b32_e32 v106, v123, v124, vcc
	v_cndmask_b32_e32 v104, v124, v122, vcc
	v_cvt_pk_bf16_f32 v103, v100, v101
	v_cvt_pk_bf16_f32 v96, v96, v97
	v_lshl_add_u64 v[100:101], v[120:121], 0, v[110:111]
	v_max_f32_e32 v94, 0, v94
	v_max_f32_e32 v95, 0, v95
	v_pk_mul_f32 v[92:93], v[92:93], v[92:93]
	v_max_f32_e32 v88, 0, v88
	v_max_f32_e32 v89, 0, v89
	v_max_f32_e32 v90, v90, v90
	v_max_f32_e32 v91, v91, v91
	v_cndmask_b32_e32 v97, v103, v96, vcc
	global_store_dwordx4 v[100:101], v[104:107], off
	v_max_f32_e32 v90, 0, v90
	v_max_f32_e32 v91, 0, v91
	v_cvt_pk_bf16_f32 v104, v92, v93
	v_pk_mul_f32 v[92:93], v[94:95], v[94:95]
	v_pk_mul_f32 v[88:89], v[88:89], v[88:89]
	ds_bpermute_b32 v97, v132, v97
	v_cvt_pk_bf16_f32 v92, v92, v93
	v_cvt_pk_bf16_f32 v93, v88, v89
	v_pk_mul_f32 v[88:89], v[90:91], v[90:91]
	v_or_b32_e32 v102, 48, v130
	v_cvt_pk_bf16_f32 v94, v88, v89
	v_cndmask_b32_e32 v89, v104, v93, vcc
	ds_bpermute_b32 v105, v132, v89
	v_max_f32_e32 v84, v84, v84
	v_max_f32_e32 v85, v85, v85
	s_waitcnt lgkmcnt(0)
	v_cndmask_b32_e32 v99, v96, v97, vcc
	v_cndmask_b32_e32 v97, v97, v103, vcc
	v_ashrrev_i32_e32 v103, 31, v102
	v_cndmask_b32_e32 v88, v92, v94, vcc
	v_max_f32_e32 v84, 0, v84
	v_max_f32_e32 v85, 0, v85
	v_max_f32_e32 v86, v86, v86
	v_max_f32_e32 v87, v87, v87
	v_max_f32_e32 v80, v80, v80
	v_max_f32_e32 v81, v81, v81
	ds_bpermute_b32 v95, v132, v88
	v_lshlrev_b64 v[88:89], 13, v[102:103]
	v_max_f32_e32 v86, 0, v86
	v_max_f32_e32 v87, 0, v87
	v_pk_mul_f32 v[84:85], v[84:85], v[84:85]
	v_max_f32_e32 v80, 0, v80
	v_max_f32_e32 v81, 0, v81
	v_max_f32_e32 v82, v82, v82
	v_max_f32_e32 v83, v83, v83
	v_lshl_add_u64 v[90:91], v[120:121], 0, v[88:89]
	v_cndmask_b32_e32 v88, v93, v105, vcc
	v_cvt_pk_bf16_f32 v93, v84, v85
	v_pk_mul_f32 v[84:85], v[86:87], v[86:87]
	v_max_f32_e32 v82, 0, v82
	v_max_f32_e32 v83, 0, v83
	v_pk_mul_f32 v[80:81], v[80:81], v[80:81]
	v_cvt_pk_bf16_f32 v84, v84, v85
	v_cvt_pk_bf16_f32 v85, v80, v81
	v_pk_mul_f32 v[80:81], v[82:83], v[82:83]
	v_cndmask_b32_e32 v82, v93, v85, vcc
	v_cvt_pk_bf16_f32 v80, v80, v81
	v_cndmask_b32_e32 v81, v84, v80, vcc
	ds_bpermute_b32 v83, v132, v81
	ds_bpermute_b32 v82, v132, v82
	v_max_f32_e32 v76, v76, v76
	v_max_f32_e32 v77, v77, v77
	v_max_f32_e32 v76, 0, v76
	v_max_f32_e32 v77, 0, v77
	v_max_f32_e32 v78, v78, v78
	v_max_f32_e32 v79, v79, v79
	v_max_f32_e32 v72, v72, v72
	v_max_f32_e32 v73, v73, v73
	v_max_f32_e32 v78, 0, v78
	v_max_f32_e32 v79, 0, v79
	v_pk_mul_f32 v[76:77], v[76:77], v[76:77]
	v_max_f32_e32 v72, 0, v72
	v_max_f32_e32 v73, 0, v73
	v_max_f32_e32 v74, v74, v74
	v_max_f32_e32 v75, v75, v75
	s_waitcnt lgkmcnt(0)
	v_cndmask_b32_e32 v81, v80, v83, vcc
	v_cndmask_b32_e32 v80, v85, v82, vcc
	v_cvt_pk_bf16_f32 v85, v76, v77
	v_pk_mul_f32 v[76:77], v[78:79], v[78:79]
	v_max_f32_e32 v74, 0, v74
	v_max_f32_e32 v75, 0, v75
	v_pk_mul_f32 v[72:73], v[72:73], v[72:73]
	v_cvt_pk_bf16_f32 v76, v76, v77
	v_cvt_pk_bf16_f32 v77, v72, v73
	v_pk_mul_f32 v[72:73], v[74:75], v[74:75]
	v_cndmask_b32_e32 v74, v85, v77, vcc
	v_cvt_pk_bf16_f32 v72, v72, v73
	v_cndmask_b32_e32 v73, v76, v72, vcc
	ds_bpermute_b32 v75, v132, v73
	ds_bpermute_b32 v74, v132, v74
	v_max_f32_e32 v68, v68, v68
	v_max_f32_e32 v69, v69, v69
	v_max_f32_e32 v68, 0, v68
	v_max_f32_e32 v69, 0, v69
	v_max_f32_e32 v70, v70, v70
	v_max_f32_e32 v71, v71, v71
	v_max_f32_e32 v64, v64, v64
	v_max_f32_e32 v65, v65, v65
	v_max_f32_e32 v70, 0, v70
	v_max_f32_e32 v71, 0, v71
	v_pk_mul_f32 v[68:69], v[68:69], v[68:69]
	v_max_f32_e32 v64, 0, v64
	v_max_f32_e32 v65, 0, v65
	v_max_f32_e32 v66, v66, v66
	v_max_f32_e32 v67, v67, v67
	s_waitcnt lgkmcnt(0)
	v_cndmask_b32_e32 v73, v72, v75, vcc
	v_cndmask_b32_e32 v72, v77, v74, vcc
	v_cvt_pk_bf16_f32 v77, v68, v69
	v_pk_mul_f32 v[68:69], v[70:71], v[70:71]
	v_max_f32_e32 v66, 0, v66
	v_max_f32_e32 v67, 0, v67
	v_pk_mul_f32 v[64:65], v[64:65], v[64:65]
	v_cvt_pk_bf16_f32 v68, v68, v69
	v_cvt_pk_bf16_f32 v69, v64, v65
	v_pk_mul_f32 v[64:65], v[66:67], v[66:67]
	v_max_f32_e32 v60, v60, v60
	v_cvt_pk_bf16_f32 v64, v64, v65
	v_cndmask_b32_e32 v65, v68, v64, vcc
	ds_bpermute_b32 v65, v132, v65
	v_max_f32_e32 v61, v61, v61
	v_max_f32_e32 v56, v56, v56
	v_max_f32_e32 v57, v57, v57
	v_max_f32_e32 v60, 0, v60
	v_max_f32_e32 v61, 0, v61
	v_max_f32_e32 v62, v62, v62
	v_max_f32_e32 v63, v63, v63
	v_max_f32_e32 v56, 0, v56
	v_max_f32_e32 v57, 0, v57
	v_max_f32_e32 v58, v58, v58
	v_max_f32_e32 v59, v59, v59
	v_max_f32_e32 v62, 0, v62
	v_max_f32_e32 v63, 0, v63
	v_pk_mul_f32 v[60:61], v[60:61], v[60:61]
	v_max_f32_e32 v58, 0, v58
	v_max_f32_e32 v59, 0, v59
	v_pk_mul_f32 v[56:57], v[56:57], v[56:57]
	s_waitcnt lgkmcnt(0)
	v_cndmask_b32_e32 v67, v64, v65, vcc
	v_cndmask_b32_e32 v65, v65, v68, vcc
	v_cvt_pk_bf16_f32 v68, v60, v61
	v_pk_mul_f32 v[60:61], v[62:63], v[62:63]
	v_cvt_pk_bf16_f32 v62, v56, v57
	v_pk_mul_f32 v[56:57], v[58:59], v[58:59]
	v_cvt_pk_bf16_f32 v61, v60, v61
	v_cvt_pk_bf16_f32 v56, v56, v57
	v_cndmask_b32_e32 v57, v61, v56, vcc
	v_cndmask_b32_e32 v58, v68, v62, vcc
	ds_bpermute_b32 v57, v132, v57
	ds_bpermute_b32 v63, v132, v58
	v_max_f32_e32 v52, v52, v52
	v_max_f32_e32 v53, v53, v53
	v_max_f32_e32 v48, v48, v48
	v_max_f32_e32 v49, v49, v49
	v_cndmask_b32_e32 v79, v83, v84, vcc
	v_cndmask_b32_e32 v78, v82, v93, vcc
	v_cndmask_b32_e32 v66, v77, v69, vcc
	v_add_u32_e32 v60, 0x80, v130
	v_max_f32_e32 v52, 0, v52
	v_max_f32_e32 v53, 0, v53
	v_max_f32_e32 v54, v54, v54
	v_max_f32_e32 v55, v55, v55
	v_max_f32_e32 v48, 0, v48
	v_max_f32_e32 v49, 0, v49
	v_max_f32_e32 v50, v50, v50
	v_max_f32_e32 v51, v51, v51
	global_store_dwordx4 v[108:109], v[78:81], off offset:256
	ds_bpermute_b32 v78, v132, v66
	s_waitcnt lgkmcnt(0)
	v_cndmask_b32_e32 v59, v56, v57, vcc
	v_cndmask_b32_e32 v57, v57, v61, vcc
	v_ashrrev_i32_e32 v61, 31, v60
	v_max_f32_e32 v54, 0, v54
	v_max_f32_e32 v55, 0, v55
	v_pk_mul_f32 v[52:53], v[52:53], v[52:53]
	v_max_f32_e32 v50, 0, v50
	v_max_f32_e32 v51, 0, v51
	v_pk_mul_f32 v[48:49], v[48:49], v[48:49]
	v_max_f32_e32 v44, v44, v44
	v_max_f32_e32 v45, v45, v45
	v_max_f32_e32 v40, v40, v40
	v_max_f32_e32 v41, v41, v41
	v_cndmask_b32_e32 v58, v62, v63, vcc
	v_cndmask_b32_e32 v56, v63, v68, vcc
	v_lshlrev_b64 v[60:61], 13, v[60:61]
	v_cvt_pk_bf16_f32 v62, v52, v53
	v_pk_mul_f32 v[52:53], v[54:55], v[54:55]
	v_cvt_pk_bf16_f32 v63, v48, v49
	v_pk_mul_f32 v[48:49], v[50:51], v[50:51]
	v_max_f32_e32 v44, 0, v44
	v_max_f32_e32 v45, 0, v45
	v_max_f32_e32 v46, v46, v46
	v_max_f32_e32 v47, v47, v47
	v_max_f32_e32 v40, 0, v40
	v_max_f32_e32 v41, 0, v41
	v_max_f32_e32 v42, v42, v42
	v_max_f32_e32 v43, v43, v43
	v_cvt_pk_bf16_f32 v55, v52, v53
	v_cvt_pk_bf16_f32 v48, v48, v49
	v_lshl_add_u64 v[52:53], v[120:121], 0, v[60:61]
	v_max_f32_e32 v46, 0, v46
	v_max_f32_e32 v47, 0, v47
	v_pk_mul_f32 v[44:45], v[44:45], v[44:45]
	v_max_f32_e32 v42, 0, v42
	v_max_f32_e32 v43, 0, v43
	v_pk_mul_f32 v[40:41], v[40:41], v[40:41]
	v_cndmask_b32_e32 v49, v55, v48, vcc
	global_store_dwordx4 v[52:53], v[56:59], off
	ds_bpermute_b32 v49, v132, v49
	v_cndmask_b32_e32 v66, v69, v78, vcc
	v_cvt_pk_bf16_f32 v56, v44, v45
	v_pk_mul_f32 v[44:45], v[46:47], v[46:47]
	v_cvt_pk_bf16_f32 v57, v40, v41
	v_pk_mul_f32 v[40:41], v[42:43], v[42:43]
	v_cvt_pk_bf16_f32 v47, v44, v45
	v_cvt_pk_bf16_f32 v40, v40, v41
	v_cndmask_b32_e32 v64, v78, v77, vcc
	v_cndmask_b32_e32 v50, v62, v63, vcc
	v_cndmask_b32_e32 v41, v47, v40, vcc
	global_store_dwordx4 v[90:91], v[64:67], off offset:256
	ds_bpermute_b32 v64, v132, v50
	ds_bpermute_b32 v41, v132, v41
	v_cndmask_b32_e32 v42, v56, v57, vcc
	v_add_u32_e32 v54, 0x90, v130
	ds_bpermute_b32 v58, v132, v42
	s_waitcnt lgkmcnt(0)
	v_cndmask_b32_e32 v51, v48, v49, vcc
	v_cndmask_b32_e32 v49, v49, v55, vcc
	v_ashrrev_i32_e32 v55, 31, v54
	v_max_f32_e32 v36, v36, v36
	v_max_f32_e32 v37, v37, v37
	v_max_f32_e32 v32, v32, v32
	v_max_f32_e32 v33, v33, v33
	v_lshlrev_b64 v[54:55], 13, v[54:55]
	v_add_u32_e32 v46, 0xa0, v130
	v_max_f32_e32 v36, 0, v36
	v_max_f32_e32 v37, 0, v37
	v_max_f32_e32 v38, v38, v38
	v_max_f32_e32 v39, v39, v39
	v_max_f32_e32 v32, 0, v32
	v_max_f32_e32 v33, 0, v33
	v_max_f32_e32 v34, v34, v34
	v_max_f32_e32 v35, v35, v35
	v_cndmask_b32_e32 v50, v63, v64, vcc
	v_cndmask_b32_e32 v48, v64, v62, vcc
	v_lshl_add_u64 v[44:45], v[120:121], 0, v[54:55]
	v_cndmask_b32_e32 v43, v40, v41, vcc
	v_cndmask_b32_e32 v41, v41, v47, vcc
	v_ashrrev_i32_e32 v47, 31, v46
	v_max_f32_e32 v38, 0, v38
	v_max_f32_e32 v39, 0, v39
	v_pk_mul_f32 v[36:37], v[36:37], v[36:37]
	v_max_f32_e32 v34, 0, v34
	v_max_f32_e32 v35, 0, v35
	v_pk_mul_f32 v[32:33], v[32:33], v[32:33]
	v_max_f32_e32 v28, v28, v28
	v_max_f32_e32 v29, v29, v29
	global_store_dwordx4 v[44:45], v[48:51], off
	v_lshlrev_b64 v[46:47], 13, v[46:47]
	v_max_f32_e32 v28, 0, v28
	v_cvt_pk_bf16_f32 v48, v36, v37
	v_pk_mul_f32 v[36:37], v[38:39], v[38:39]
	v_cvt_pk_bf16_f32 v49, v32, v33
	v_pk_mul_f32 v[32:33], v[34:35], v[34:35]
	v_max_f32_e32 v29, 0, v29
	v_max_f32_e32 v30, v30, v30
	v_max_f32_e32 v31, v31, v31
	v_max_f32_e32 v24, v24, v24
	v_max_f32_e32 v25, v25, v25
	v_cndmask_b32_e32 v42, v57, v58, vcc
	v_cndmask_b32_e32 v40, v58, v56, vcc
	v_cvt_pk_bf16_f32 v39, v36, v37
	v_cvt_pk_bf16_f32 v32, v32, v33
	v_lshl_add_u64 v[36:37], v[120:121], 0, v[46:47]
	v_max_f32_e32 v30, 0, v30
	v_max_f32_e32 v31, 0, v31
	v_pk_mul_f32 v[28:29], v[28:29], v[28:29]
	v_max_f32_e32 v24, 0, v24
	v_max_f32_e32 v25, 0, v25
	v_max_f32_e32 v26, v26, v26
	v_max_f32_e32 v27, v27, v27
	v_cndmask_b32_e32 v33, v39, v32, vcc
	global_store_dwordx4 v[36:37], v[40:43], off
	v_max_f32_e32 v26, 0, v26
	v_max_f32_e32 v27, 0, v27
	v_cvt_pk_bf16_f32 v40, v28, v29
	v_pk_mul_f32 v[28:29], v[30:31], v[30:31]
	v_pk_mul_f32 v[24:25], v[24:25], v[24:25]
	ds_bpermute_b32 v33, v132, v33
	v_cvt_pk_bf16_f32 v28, v28, v29
	v_cvt_pk_bf16_f32 v29, v24, v25
	v_pk_mul_f32 v[24:25], v[26:27], v[26:27]
	v_add_u32_e32 v38, 0xb0, v130
	v_cvt_pk_bf16_f32 v30, v24, v25
	v_cndmask_b32_e32 v25, v40, v29, vcc
	ds_bpermute_b32 v41, v132, v25
	v_max_f32_e32 v20, v20, v20
	v_max_f32_e32 v21, v21, v21
	s_waitcnt lgkmcnt(0)
	v_cndmask_b32_e32 v35, v32, v33, vcc
	v_cndmask_b32_e32 v33, v33, v39, vcc
	v_ashrrev_i32_e32 v39, 31, v38
	v_cndmask_b32_e32 v24, v28, v30, vcc
	v_max_f32_e32 v20, 0, v20
	v_max_f32_e32 v21, 0, v21
	v_max_f32_e32 v22, v22, v22
	v_max_f32_e32 v23, v23, v23
	v_max_f32_e32 v16, v16, v16
	v_max_f32_e32 v17, v17, v17
	ds_bpermute_b32 v31, v132, v24
	v_lshlrev_b64 v[24:25], 13, v[38:39]
	v_max_f32_e32 v22, 0, v22
	v_max_f32_e32 v23, 0, v23
	v_pk_mul_f32 v[20:21], v[20:21], v[20:21]
	v_max_f32_e32 v16, 0, v16
	v_max_f32_e32 v17, 0, v17
	v_max_f32_e32 v18, v18, v18
	v_max_f32_e32 v19, v19, v19
	v_lshl_add_u64 v[26:27], v[120:121], 0, v[24:25]
	v_cndmask_b32_e32 v24, v29, v41, vcc
	v_cvt_pk_bf16_f32 v29, v20, v21
	v_pk_mul_f32 v[20:21], v[22:23], v[22:23]
	v_max_f32_e32 v18, 0, v18
	v_max_f32_e32 v19, 0, v19
	v_pk_mul_f32 v[16:17], v[16:17], v[16:17]
	v_cvt_pk_bf16_f32 v20, v20, v21
	v_cvt_pk_bf16_f32 v21, v16, v17
	v_pk_mul_f32 v[16:17], v[18:19], v[18:19]
	v_cndmask_b32_e32 v18, v29, v21, vcc
	v_cvt_pk_bf16_f32 v16, v16, v17
	v_cndmask_b32_e32 v17, v20, v16, vcc
	ds_bpermute_b32 v19, v132, v17
	ds_bpermute_b32 v18, v132, v18
	v_max_f32_e32 v12, v12, v12
	v_max_f32_e32 v13, v13, v13
	v_max_f32_e32 v12, 0, v12
	v_max_f32_e32 v13, 0, v13
	v_max_f32_e32 v14, v14, v14
	v_max_f32_e32 v15, v15, v15
	v_max_f32_e32 v8, v8, v8
	v_max_f32_e32 v9, v9, v9
	v_max_f32_e32 v14, 0, v14
	v_max_f32_e32 v15, 0, v15
	v_pk_mul_f32 v[12:13], v[12:13], v[12:13]
	v_max_f32_e32 v8, 0, v8
	v_max_f32_e32 v9, 0, v9
	v_max_f32_e32 v10, v10, v10
	v_max_f32_e32 v11, v11, v11
	s_waitcnt lgkmcnt(0)
	v_cndmask_b32_e32 v17, v16, v19, vcc
	v_cndmask_b32_e32 v16, v21, v18, vcc
	v_cvt_pk_bf16_f32 v21, v12, v13
	v_pk_mul_f32 v[12:13], v[14:15], v[14:15]
	v_max_f32_e32 v10, 0, v10
	v_max_f32_e32 v11, 0, v11
	v_pk_mul_f32 v[8:9], v[8:9], v[8:9]
	v_cvt_pk_bf16_f32 v12, v12, v13
	v_cvt_pk_bf16_f32 v13, v8, v9
	v_pk_mul_f32 v[8:9], v[10:11], v[10:11]
	v_cndmask_b32_e32 v10, v21, v13, vcc
	v_cvt_pk_bf16_f32 v8, v8, v9
	v_cndmask_b32_e32 v9, v12, v8, vcc
	ds_bpermute_b32 v11, v132, v9
	ds_bpermute_b32 v10, v132, v10
	v_max_f32_e32 v4, v4, v4
	v_max_f32_e32 v5, v5, v5
	v_max_f32_e32 v4, 0, v4
	v_max_f32_e32 v5, 0, v5
	v_max_f32_e32 v6, v6, v6
	v_max_f32_e32 v7, v7, v7
	v_max_f32_e32 v0, v0, v0
	v_max_f32_e32 v1, v1, v1
	v_max_f32_e32 v6, 0, v6
	v_max_f32_e32 v7, 0, v7
	v_pk_mul_f32 v[4:5], v[4:5], v[4:5]
	v_max_f32_e32 v0, 0, v0
	v_max_f32_e32 v1, 0, v1
	v_max_f32_e32 v2, v2, v2
	v_max_f32_e32 v3, v3, v3
	s_waitcnt lgkmcnt(0)
	v_cndmask_b32_e32 v9, v8, v11, vcc
	v_cndmask_b32_e32 v8, v13, v10, vcc
	v_cvt_pk_bf16_f32 v13, v4, v5
	v_pk_mul_f32 v[4:5], v[6:7], v[6:7]
	v_max_f32_e32 v2, 0, v2
	v_max_f32_e32 v3, 0, v3
	v_pk_mul_f32 v[0:1], v[0:1], v[0:1]
	v_cvt_pk_bf16_f32 v4, v4, v5
	v_cvt_pk_bf16_f32 v5, v0, v1
	v_pk_mul_f32 v[0:1], v[2:3], v[2:3]
	v_cndmask_b32_e32 v98, v112, v113, vcc
	v_cvt_pk_bf16_f32 v0, v0, v1
	v_cndmask_b32_e32 v34, v48, v49, vcc
	v_cndmask_b32_e32 v15, v19, v20, vcc
	v_cndmask_b32_e32 v14, v18, v29, vcc
	v_cndmask_b32_e32 v1, v4, v0, vcc
	v_cndmask_b32_e32 v2, v13, v5, vcc
	ds_bpermute_b32 v114, v132, v98
	ds_bpermute_b32 v50, v132, v34
	global_store_dwordx4 v[44:45], v[14:17], off offset:256
	ds_bpermute_b32 v1, v132, v1
	ds_bpermute_b32 v14, v132, v2
	s_lshr_b32 s0, s90, 3
	s_waitcnt lgkmcnt(0)
	v_cndmask_b32_e32 v98, v113, v114, vcc
	v_cndmask_b32_e32 v96, v114, v112, vcc
	v_cndmask_b32_e32 v89, v94, v95, vcc
	v_cndmask_b32_e32 v87, v95, v92, vcc
	v_cndmask_b32_e32 v86, v105, v104, vcc
	v_cndmask_b32_e32 v71, v75, v76, vcc
	v_cndmask_b32_e32 v70, v74, v85, vcc
	v_cndmask_b32_e32 v34, v49, v50, vcc
	v_cndmask_b32_e32 v32, v50, v48, vcc
	v_cndmask_b32_e32 v25, v30, v31, vcc
	v_cndmask_b32_e32 v23, v31, v28, vcc
	v_cndmask_b32_e32 v22, v41, v40, vcc
	v_cndmask_b32_e32 v7, v11, v12, vcc
	v_cndmask_b32_e32 v6, v10, v21, vcc
	v_cndmask_b32_e32 v3, v0, v1, vcc
	v_cndmask_b32_e32 v2, v5, v14, vcc
	v_cndmask_b32_e32 v1, v1, v4, vcc
	v_cndmask_b32_e32 v0, v14, v13, vcc
	s_add_i32 s38, s38, s0
	s_and_b64 vcc, exec, s[58:59]
	global_store_dwordx4 v[90:91], v[96:99], off
	global_store_dwordx4 v[116:117], v[86:89], off offset:256
	global_store_dwordx4 v[100:101], v[70:73], off offset:256
	global_store_dwordx4 v[26:27], v[32:35], off
	global_store_dwordx4 v[52:53], v[22:25], off offset:256
	global_store_dwordx4 v[36:37], v[6:9], off offset:256
	global_store_dwordx4 v[26:27], v[0:3], off offset:256
	s_waitcnt vmcnt(16)
	s_barrier
	s_cbranch_vccnz .LBB0_1666

.LBB0_1655:
	s_waitcnt vmcnt(16)
	s_cbranch_execz .LBB0_1659
	s_branch .LBB0_1660

.LBB0_1658:
	s_andn2_b64 vcc, exec, s[60:61]
	s_cbranch_vccnz .LBB0_1660
.LBB0_1659:
	s_waitcnt vmcnt(0)
.LBB0_1660:
	v_add_u32_e32 v2, v0, v2
	v_and_b32_e32 v2, 0xfffffc00, v2
	v_sub_u32_e32 v2, v0, v2
	v_lshrrev_b32_e32 v5, 4, v2
	v_add_u32_e32 v3, v128, v3
	v_bitop3_b32 v5, v5, v2, 32 bitop3:0x6c
	v_ashrrev_i32_e32 v2, 31, v2
	v_ashrrev_i32_e32 v3, 6, v3
	v_lshrrev_b32_e32 v2, 26, v2
	v_lshlrev_b32_e32 v6, 3, v3
	v_add_u32_e32 v2, v5, v2
	s_and_b32 s0, s38, 3
	v_and_b32_e32 v6, -16, v6
	v_ashrrev_i32_e32 v7, 6, v2
	s_lshl_b32 s0, s0, 18
	v_add_u32_e32 v2, v7, v6
	v_mul_i32_i24_e32 v6, 64, v7
	s_add_i32 s0, s63, s0
	v_lshlrev_b32_e32 v3, 5, v3
	v_sub_u32_e32 v5, v5, v6
	s_lshl_b32 s6, s0, 1
	s_lshl_b32 s0, s71, 19
	v_and_b32_e32 v3, 32, v3
	v_ashrrev_i16_sdwa v5, v150, sext(v5) dst_sel:DWORD dst_unused:UNUSED_PAD src0_sel:DWORD src1_sel:BYTE_0
	s_add_u32 s0, s57, s0
	v_add_u32_sdwa v138, v3, sext(v5) dst_sel:DWORD dst_unused:UNUSED_PAD src0_sel:DWORD src1_sel:WORD_0
	v_ashrrev_i32_e32 v3, 31, v2
	s_addc_u32 s1, s62, 0
	v_lshlrev_b64 v[130:131], 11, v[2:3]
	v_ashrrev_i32_e32 v139, 31, v138
	v_lshl_add_u64 v[2:3], s[0:1], 0, v[130:131]
	v_lshlrev_b64 v[132:133], 1, v[138:139]
	v_add_u32_e32 v167, s66, v0
	v_lshl_add_u64 v[2:3], v[2:3], 0, v[132:133]
	v_readfirstlane_b32 s2, v167
	v_lshl_add_u64 v[2:3], v[2:3], 0, s[10:11]
	s_mov_b32 m0, s2
	s_barrier
	global_load_lds_dwordx4 v[2:3], off
	v_ashrrev_i32_e32 v2, 31, v1
	v_lshrrev_b32_e32 v2, 22, v2
	v_add_u32_e32 v2, v1, v2
	v_ashrrev_i32_e32 v3, 10, v2
	v_mul_i32_i24_e32 v2, 0x400, v3
	v_sub_u32_e32 v2, v1, v2
	v_lshrrev_b32_e32 v5, 4, v2
	v_bitop3_b32 v5, v5, v2, 32 bitop3:0x6c
	v_ashrrev_i32_e32 v6, 31, v5
	v_lshrrev_b32_e32 v6, 26, v6
	v_add_u32_e32 v6, v5, v6
	v_lshlrev_b32_e32 v2, 3, v3
	v_ashrrev_i32_e32 v7, 6, v6
	v_and_b32_e32 v6, 0xc0, v6
	v_and_b32_e32 v2, -16, v2
	v_lshlrev_b32_e32 v3, 5, v3
	v_sub_u32_e32 v5, v5, v6
	v_add_u32_e32 v2, v7, v2
	v_and_b32_e32 v3, 32, v3
	v_ashrrev_i16_sdwa v5, v150, sext(v5) dst_sel:DWORD dst_unused:UNUSED_PAD src0_sel:DWORD src1_sel:BYTE_0
	v_add_u32_sdwa v140, v3, sext(v5) dst_sel:DWORD dst_unused:UNUSED_PAD src0_sel:DWORD src1_sel:WORD_0
	v_ashrrev_i32_e32 v3, 31, v2
	v_lshlrev_b64 v[134:135], 11, v[2:3]
	v_ashrrev_i32_e32 v141, 31, v140
	s_ashr_i32 s37, s36, 31
	v_lshl_add_u64 v[2:3], s[0:1], 0, v[134:135]
	v_lshlrev_b64 v[136:137], 1, v[140:141]
	v_add_u32_e32 v5, s66, v1
	s_lshl_b64 s[40:41], s[36:37], 11
	v_lshl_add_u64 v[2:3], v[2:3], 0, v[136:137]
	v_readfirstlane_b32 s2, v5
	s_add_u32 s42, s39, s40
	v_lshl_add_u64 v[2:3], v[2:3], 0, s[10:11]
	s_mov_b32 m0, s2
	s_addc_u32 s43, s46, s41
	global_load_lds_dwordx4 v[2:3], off
	v_lshl_add_u64 v[2:3], s[42:43], 0, v[130:131]
	v_add_u32_e32 v169, 0x8000, v152
	v_lshl_add_u64 v[2:3], v[2:3], 0, v[132:133]
	v_readfirstlane_b32 s2, v169
	v_lshl_add_u64 v[2:3], v[2:3], 0, s[10:11]
	s_mov_b32 m0, s2
	v_add_u32_e32 v170, 0xa000, v152
	global_load_lds_dwordx4 v[2:3], off
	v_lshl_add_u64 v[2:3], s[42:43], 0, v[134:135]
	v_lshl_add_u64 v[2:3], v[2:3], 0, v[136:137]
	v_readfirstlane_b32 s2, v170
	s_add_u32 s0, s0, 0x40080
	v_lshl_add_u64 v[2:3], v[2:3], 0, s[10:11]
	s_mov_b32 m0, s2
	s_addc_u32 s1, s1, 0
	v_add_u32_e32 v171, s67, v0
	global_load_lds_dwordx4 v[2:3], off
	v_lshl_add_u64 v[2:3], s[0:1], 0, v[130:131]
	v_readfirstlane_b32 s2, v171
	v_lshl_add_u64 v[2:3], v[2:3], 0, v[132:133]
	s_mov_b32 m0, s2
	v_add_u32_e32 v0, s67, v1
	global_load_lds_dwordx4 v[2:3], off
	v_lshl_add_u64 v[2:3], s[0:1], 0, v[134:135]
	v_readfirstlane_b32 s0, v0
	v_lshl_add_u64 v[2:3], v[2:3], 0, v[136:137]
	s_mov_b32 m0, s0
	v_and_b32_e32 v156, 15, v128
	global_load_lds_dwordx4 v[2:3], off
	v_bfe_u32 v155, v128, 4, 2
	v_lshlrev_b32_e32 v2, 2, v128
	v_lshlrev_b32_e32 v0, 4, v155
	v_lshlrev_b32_e32 v1, 6, v156
	v_and_b32_e32 v2, 32, v2
	v_bitop3_b32 v1, v0, v2, v1 bitop3:0x36
	v_add_u32_e32 v6, s64, v1
	v_add_u32_e32 v7, s65, v1
	v_add_u32_e32 v8, s66, v1
	v_add_u32_e32 v9, s67, v1
	v_add_u32_e32 v10, 0, v1
	v_lshlrev_b32_e32 v1, 6, v128
	v_and_or_b32 v0, v1, s68, v0
	v_bfe_u32 v154, v128, 6, 2
	s_waitcnt vmcnt(22)
	v_lshlrev_b32_e32 v157, 6, v4
	v_lshlrev_b32_e32 v4, 13, v4
	v_xad_u32 v11, v0, v2, 0
	v_lshl_add_u64 v[0:1], v[130:131], 0, v[132:133]
	v_lshlrev_b32_e32 v5, 12, v154
	v_or_b32_e32 v12, 0x800, v4
	v_or_b32_e32 v13, 0x1000, v4
	v_or_b32_e32 v14, 0x1800, v4
	v_lshl_add_u64 v[142:143], v[0:1], 0, s[6:7]
	v_lshl_add_u64 v[2:3], v[134:135], 0, v[136:137]
	v_lshl_add_u64 v[146:147], v[0:1], 0, s[40:41]
	v_mov_b32_e32 v0, 0
	v_lshl_add_u64 v[144:145], v[2:3], 0, s[6:7]
	v_lshl_add_u64 v[148:149], v[2:3], 0, s[40:41]
	s_mov_b32 s0, -2
	v_add_u32_e32 v172, v6, v5
	v_add_u32_e32 v161, v10, v4
	v_add_u32_e32 v160, v11, v12
	v_add_u32_e32 v159, v11, v13
	v_add_u32_e32 v158, v11, v14
	v_add_u32_e32 v168, v7, v5
	v_add_u32_e32 v163, v8, v5
	v_add_u32_e32 v162, v9, v5
	v_mov_b32_e32 v1, v0
	v_mov_b32_e32 v2, v0
	v_mov_b32_e32 v3, v0
	v_mov_b32_e32 v4, v0
	v_mov_b32_e32 v5, v0
	v_mov_b32_e32 v6, v0
	v_mov_b32_e32 v7, v0
	v_mov_b32_e32 v8, v0
	v_mov_b32_e32 v9, v0
	v_mov_b32_e32 v10, v0
	v_mov_b32_e32 v11, v0
	v_mov_b32_e32 v12, v0
	v_mov_b32_e32 v13, v0
	v_mov_b32_e32 v14, v0
	v_mov_b32_e32 v15, v0
	v_mov_b32_e32 v16, v0
	v_mov_b32_e32 v17, v0
	v_mov_b32_e32 v18, v0
	v_mov_b32_e32 v19, v0
	v_mov_b32_e32 v20, v0
	v_mov_b32_e32 v21, v0
	v_mov_b32_e32 v22, v0
	v_mov_b32_e32 v23, v0
	v_mov_b32_e32 v24, v0
	v_mov_b32_e32 v25, v0
	v_mov_b32_e32 v26, v0
	v_mov_b32_e32 v27, v0
	v_mov_b32_e32 v28, v0
	v_mov_b32_e32 v29, v0
	v_mov_b32_e32 v30, v0
	v_mov_b32_e32 v31, v0
	v_mov_b32_e32 v32, v0
	v_mov_b32_e32 v33, v0
	v_mov_b32_e32 v34, v0
	v_mov_b32_e32 v35, v0
	v_mov_b32_e32 v36, v0
	v_mov_b32_e32 v37, v0
	v_mov_b32_e32 v38, v0
	v_mov_b32_e32 v39, v0
	v_mov_b32_e32 v40, v0
	v_mov_b32_e32 v41, v0
	v_mov_b32_e32 v42, v0
	v_mov_b32_e32 v43, v0
	v_mov_b32_e32 v44, v0
	v_mov_b32_e32 v45, v0
	v_mov_b32_e32 v46, v0
	v_mov_b32_e32 v47, v0
	v_mov_b32_e32 v48, v0
	v_mov_b32_e32 v49, v0
	v_mov_b32_e32 v50, v0
	v_mov_b32_e32 v51, v0
	v_mov_b32_e32 v52, v0
	v_mov_b32_e32 v53, v0
	v_mov_b32_e32 v54, v0
	v_mov_b32_e32 v55, v0
	v_mov_b32_e32 v56, v0
	v_mov_b32_e32 v57, v0
	v_mov_b32_e32 v58, v0
	v_mov_b32_e32 v59, v0
	v_mov_b32_e32 v60, v0
	v_mov_b32_e32 v61, v0
	v_mov_b32_e32 v62, v0
	v_mov_b32_e32 v63, v0
	v_mov_b32_e32 v64, v0
	v_mov_b32_e32 v65, v0
	v_mov_b32_e32 v66, v0
	v_mov_b32_e32 v67, v0
	v_mov_b32_e32 v68, v0
	v_mov_b32_e32 v69, v0
	v_mov_b32_e32 v70, v0
	v_mov_b32_e32 v71, v0
	v_mov_b32_e32 v72, v0
	v_mov_b32_e32 v73, v0
	v_mov_b32_e32 v74, v0
	v_mov_b32_e32 v75, v0
	v_mov_b32_e32 v76, v0
	v_mov_b32_e32 v77, v0
	v_mov_b32_e32 v78, v0
	v_mov_b32_e32 v79, v0
	v_mov_b32_e32 v80, v0
	v_mov_b32_e32 v81, v0
	v_mov_b32_e32 v82, v0
	v_mov_b32_e32 v83, v0
	v_mov_b32_e32 v84, v0
	v_mov_b32_e32 v85, v0
	v_mov_b32_e32 v86, v0
	v_mov_b32_e32 v87, v0
	v_mov_b32_e32 v88, v0
	v_mov_b32_e32 v89, v0
	v_mov_b32_e32 v90, v0
	v_mov_b32_e32 v91, v0
	v_mov_b32_e32 v92, v0
	v_mov_b32_e32 v93, v0
	v_mov_b32_e32 v94, v0
	v_mov_b32_e32 v95, v0
	v_mov_b32_e32 v96, v0
	v_mov_b32_e32 v97, v0
	v_mov_b32_e32 v98, v0
	v_mov_b32_e32 v99, v0
	v_mov_b32_e32 v100, v0
	v_mov_b32_e32 v101, v0
	v_mov_b32_e32 v102, v0
	v_mov_b32_e32 v103, v0
	v_mov_b32_e32 v104, v0
	v_mov_b32_e32 v105, v0
	v_mov_b32_e32 v106, v0
	v_mov_b32_e32 v107, v0
	v_mov_b32_e32 v108, v0
	v_mov_b32_e32 v109, v0
	v_mov_b32_e32 v110, v0
	v_mov_b32_e32 v111, v0
	v_mov_b32_e32 v112, v0
	v_mov_b32_e32 v113, v0
	v_mov_b32_e32 v114, v0
	v_mov_b32_e32 v115, v0
	v_mov_b32_e32 v116, v0
	v_mov_b32_e32 v117, v0
	v_mov_b32_e32 v118, v0
	v_mov_b32_e32 v119, v0
	v_mov_b32_e32 v120, v0
	v_mov_b32_e32 v121, v0
	v_mov_b32_e32 v122, v0
	v_mov_b32_e32 v123, v0
	v_mov_b32_e32 v124, v0
	v_mov_b32_e32 v125, v0
	v_mov_b32_e32 v126, v0
	v_mov_b32_e32 v127, v0
	s_barrier

.LBB0_2906:
	s_or_b64 exec, exec, s[44:45]
	v_and_b32_e32 v134, 64, v165
	v_xor_b32_e32 v132, 16, v165
	v_add_u32_e32 v134, 64, v134
	v_max_f32_e32 v124, v124, v124
	v_max_f32_e32 v125, v125, v125
	v_and_b32_e32 v128, 16, v128
	v_lshlrev_b32_e32 v133, 2, v155
	v_cmp_lt_i32_e32 vcc, v132, v134
	v_max_f32_e32 v124, 0, v124
	v_max_f32_e32 v125, 0, v125
	v_max_f32_e32 v126, v126, v126
	v_max_f32_e32 v127, v127, v127
	v_max_f32_e32 v120, v120, v120
	v_max_f32_e32 v121, v121, v121
	v_cndmask_b32_e32 v132, v165, v132, vcc
	v_add_u32_e32 v134, 12, v133
	v_cmp_eq_u32_e32 vcc, 0, v128
	v_max_f32_e32 v126, 0, v126
	v_max_f32_e32 v127, 0, v127
	v_pk_mul_f32 v[124:125], v[124:125], v[124:125]
	v_max_f32_e32 v120, 0, v120
	v_max_f32_e32 v121, 0, v121
	v_max_f32_e32 v122, v122, v122
	v_max_f32_e32 v123, v123, v123
	v_cndmask_b32_e32 v128, v134, v133, vcc
	v_cvt_pk_bf16_f32 v133, v124, v125
	v_pk_mul_f32 v[124:125], v[126:127], v[126:127]
	v_max_f32_e32 v122, 0, v122
	v_max_f32_e32 v123, 0, v123
	v_pk_mul_f32 v[120:121], v[120:121], v[120:121]
	v_cvt_pk_bf16_f32 v126, v124, v125
	v_cvt_pk_bf16_f32 v124, v120, v121
	v_pk_mul_f32 v[120:121], v[122:123], v[122:123]
	v_lshlrev_b32_e32 v132, 2, v132
	v_cvt_pk_bf16_f32 v122, v120, v121
	v_cndmask_b32_e32 v120, v126, v122, vcc
	v_cndmask_b32_e32 v121, v133, v124, vcc
	ds_bpermute_b32 v123, v132, v120
	ds_bpermute_b32 v127, v132, v121
	s_lshl_b32 s4, s61, 8
	v_or_b32_e32 v130, s36, v156
	v_lshlrev_b32_e32 v131, 5, v154
	v_max_f32_e32 v116, v116, v116
	v_max_f32_e32 v117, v117, v117
	v_max_f32_e32 v112, v112, v112
	v_max_f32_e32 v113, v113, v113
	v_add_u32_e32 v130, v130, v157
	v_or3_b32 v120, v131, s4, v128
	v_max_f32_e32 v116, 0, v116
	v_max_f32_e32 v117, 0, v117
	v_max_f32_e32 v118, v118, v118
	v_max_f32_e32 v119, v119, v119
	v_max_f32_e32 v112, 0, v112
	v_max_f32_e32 v113, 0, v113
	v_max_f32_e32 v114, v114, v114
	v_max_f32_e32 v115, v115, v115
	v_lshlrev_b32_e32 v128, 1, v120
	v_ashrrev_i32_e32 v131, 31, v130
	v_max_f32_e32 v118, 0, v118
	v_max_f32_e32 v119, 0, v119
	v_pk_mul_f32 v[116:117], v[116:117], v[116:117]
	v_max_f32_e32 v114, 0, v114
	v_max_f32_e32 v115, 0, v115
	v_pk_mul_f32 v[112:113], v[112:113], v[112:113]
	v_max_f32_e32 v108, v108, v108
	v_max_f32_e32 v109, v109, v109
	v_max_f32_e32 v104, v104, v104
	v_max_f32_e32 v105, v105, v105
	v_lshl_add_u64 v[120:121], s[8:9], 0, v[128:129]
	s_waitcnt lgkmcnt(0)
	v_cndmask_b32_e32 v125, v122, v123, vcc
	v_cndmask_b32_e32 v124, v124, v127, vcc
	v_cndmask_b32_e32 v123, v123, v126, vcc
	v_cndmask_b32_e32 v122, v127, v133, vcc
	v_lshlrev_b64 v[126:127], 13, v[130:131]
	v_cvt_pk_bf16_f32 v128, v116, v117
	v_pk_mul_f32 v[116:117], v[118:119], v[118:119]
	v_cvt_pk_bf16_f32 v131, v112, v113
	v_pk_mul_f32 v[112:113], v[114:115], v[114:115]
	v_max_f32_e32 v108, 0, v108
	v_max_f32_e32 v109, 0, v109
	v_max_f32_e32 v110, v110, v110
	v_max_f32_e32 v111, v111, v111
	v_max_f32_e32 v104, 0, v104
	v_max_f32_e32 v105, 0, v105
	v_max_f32_e32 v106, v106, v106
	v_max_f32_e32 v107, v107, v107
	v_cvt_pk_bf16_f32 v119, v116, v117
	v_cvt_pk_bf16_f32 v112, v112, v113
	v_lshl_add_u64 v[116:117], v[120:121], 0, v[126:127]
	v_max_f32_e32 v110, 0, v110
	v_max_f32_e32 v111, 0, v111
	v_pk_mul_f32 v[108:109], v[108:109], v[108:109]
	v_max_f32_e32 v106, 0, v106
	v_max_f32_e32 v107, 0, v107
	v_pk_mul_f32 v[104:105], v[104:105], v[104:105]
	v_cndmask_b32_e32 v113, v119, v112, vcc
	global_store_dwordx4 v[116:117], v[122:125], off
	ds_bpermute_b32 v113, v132, v113
	v_cndmask_b32_e32 v114, v128, v131, vcc
	v_cvt_pk_bf16_f32 v122, v108, v109
	v_pk_mul_f32 v[108:109], v[110:111], v[110:111]
	v_cvt_pk_bf16_f32 v123, v104, v105
	v_pk_mul_f32 v[104:105], v[106:107], v[106:107]
	v_cvt_pk_bf16_f32 v111, v108, v109
	v_cvt_pk_bf16_f32 v104, v104, v105
	v_cndmask_b32_e32 v105, v111, v104, vcc
	ds_bpermute_b32 v133, v132, v114
	ds_bpermute_b32 v105, v132, v105
	v_cndmask_b32_e32 v106, v122, v123, vcc
	v_or_b32_e32 v118, 16, v130
	ds_bpermute_b32 v124, v132, v106
	s_waitcnt lgkmcnt(0)
	v_cndmask_b32_e32 v115, v112, v113, vcc
	v_cndmask_b32_e32 v113, v113, v119, vcc
	v_ashrrev_i32_e32 v119, 31, v118
	v_max_f32_e32 v100, v100, v100
	v_max_f32_e32 v101, v101, v101
	v_max_f32_e32 v96, v96, v96
	v_max_f32_e32 v97, v97, v97
	v_lshlrev_b64 v[118:119], 13, v[118:119]
	v_or_b32_e32 v110, 32, v130
	v_max_f32_e32 v100, 0, v100
	v_max_f32_e32 v101, 0, v101
	v_max_f32_e32 v102, v102, v102
	v_max_f32_e32 v103, v103, v103
	v_max_f32_e32 v96, 0, v96
	v_max_f32_e32 v97, 0, v97
	v_max_f32_e32 v98, v98, v98
	v_max_f32_e32 v99, v99, v99
	v_cndmask_b32_e32 v114, v131, v133, vcc
	v_cndmask_b32_e32 v112, v133, v128, vcc
	v_lshl_add_u64 v[108:109], v[120:121], 0, v[118:119]
	v_cndmask_b32_e32 v107, v104, v105, vcc
	v_cndmask_b32_e32 v105, v105, v111, vcc
	v_ashrrev_i32_e32 v111, 31, v110
	v_max_f32_e32 v102, 0, v102
	v_max_f32_e32 v103, 0, v103
	v_pk_mul_f32 v[100:101], v[100:101], v[100:101]
	v_max_f32_e32 v98, 0, v98
	v_max_f32_e32 v99, 0, v99
	v_pk_mul_f32 v[96:97], v[96:97], v[96:97]
	v_max_f32_e32 v92, v92, v92
	v_max_f32_e32 v93, v93, v93
	global_store_dwordx4 v[108:109], v[112:115], off
	v_lshlrev_b64 v[110:111], 13, v[110:111]
	v_max_f32_e32 v92, 0, v92
	v_cvt_pk_bf16_f32 v112, v100, v101
	v_pk_mul_f32 v[100:101], v[102:103], v[102:103]
	v_cvt_pk_bf16_f32 v113, v96, v97
	v_pk_mul_f32 v[96:97], v[98:99], v[98:99]
	v_max_f32_e32 v93, 0, v93
	v_max_f32_e32 v94, v94, v94
	v_max_f32_e32 v95, v95, v95
	v_max_f32_e32 v88, v88, v88
	v_max_f32_e32 v89, v89, v89
	v_cndmask_b32_e32 v106, v123, v124, vcc
	v_cndmask_b32_e32 v104, v124, v122, vcc
	v_cvt_pk_bf16_f32 v103, v100, v101
	v_cvt_pk_bf16_f32 v96, v96, v97
	v_lshl_add_u64 v[100:101], v[120:121], 0, v[110:111]
	v_max_f32_e32 v94, 0, v94
	v_max_f32_e32 v95, 0, v95
	v_pk_mul_f32 v[92:93], v[92:93], v[92:93]
	v_max_f32_e32 v88, 0, v88
	v_max_f32_e32 v89, 0, v89
	v_max_f32_e32 v90, v90, v90
	v_max_f32_e32 v91, v91, v91
	v_cndmask_b32_e32 v97, v103, v96, vcc
	global_store_dwordx4 v[100:101], v[104:107], off
	v_max_f32_e32 v90, 0, v90
	v_max_f32_e32 v91, 0, v91
	v_cvt_pk_bf16_f32 v104, v92, v93
	v_pk_mul_f32 v[92:93], v[94:95], v[94:95]
	v_pk_mul_f32 v[88:89], v[88:89], v[88:89]
	ds_bpermute_b32 v97, v132, v97
	v_cvt_pk_bf16_f32 v92, v92, v93
	v_cvt_pk_bf16_f32 v93, v88, v89
	v_pk_mul_f32 v[88:89], v[90:91], v[90:91]
	v_or_b32_e32 v102, 48, v130
	v_cvt_pk_bf16_f32 v94, v88, v89
	v_cndmask_b32_e32 v89, v104, v93, vcc
	ds_bpermute_b32 v105, v132, v89
	v_max_f32_e32 v84, v84, v84
	v_max_f32_e32 v85, v85, v85
	s_waitcnt lgkmcnt(0)
	v_cndmask_b32_e32 v99, v96, v97, vcc
	v_cndmask_b32_e32 v97, v97, v103, vcc
	v_ashrrev_i32_e32 v103, 31, v102
	v_cndmask_b32_e32 v88, v92, v94, vcc
	v_max_f32_e32 v84, 0, v84
	v_max_f32_e32 v85, 0, v85
	v_max_f32_e32 v86, v86, v86
	v_max_f32_e32 v87, v87, v87
	v_max_f32_e32 v80, v80, v80
	v_max_f32_e32 v81, v81, v81
	ds_bpermute_b32 v95, v132, v88
	v_lshlrev_b64 v[88:89], 13, v[102:103]
	v_max_f32_e32 v86, 0, v86
	v_max_f32_e32 v87, 0, v87
	v_pk_mul_f32 v[84:85], v[84:85], v[84:85]
	v_max_f32_e32 v80, 0, v80
	v_max_f32_e32 v81, 0, v81
	v_max_f32_e32 v82, v82, v82
	v_max_f32_e32 v83, v83, v83
	v_lshl_add_u64 v[90:91], v[120:121], 0, v[88:89]
	v_cndmask_b32_e32 v88, v93, v105, vcc
	v_cvt_pk_bf16_f32 v93, v84, v85
	v_pk_mul_f32 v[84:85], v[86:87], v[86:87]
	v_max_f32_e32 v82, 0, v82
	v_max_f32_e32 v83, 0, v83
	v_pk_mul_f32 v[80:81], v[80:81], v[80:81]
	v_cvt_pk_bf16_f32 v84, v84, v85
	v_cvt_pk_bf16_f32 v85, v80, v81
	v_pk_mul_f32 v[80:81], v[82:83], v[82:83]
	v_cndmask_b32_e32 v82, v93, v85, vcc
	v_cvt_pk_bf16_f32 v80, v80, v81
	v_cndmask_b32_e32 v81, v84, v80, vcc
	ds_bpermute_b32 v83, v132, v81
	ds_bpermute_b32 v82, v132, v82
	v_max_f32_e32 v76, v76, v76
	v_max_f32_e32 v77, v77, v77
	v_max_f32_e32 v76, 0, v76
	v_max_f32_e32 v77, 0, v77
	v_max_f32_e32 v78, v78, v78
	v_max_f32_e32 v79, v79, v79
	v_max_f32_e32 v72, v72, v72
	v_max_f32_e32 v73, v73, v73
	v_max_f32_e32 v78, 0, v78
	v_max_f32_e32 v79, 0, v79
	v_pk_mul_f32 v[76:77], v[76:77], v[76:77]
	v_max_f32_e32 v72, 0, v72
	v_max_f32_e32 v73, 0, v73
	v_max_f32_e32 v74, v74, v74
	v_max_f32_e32 v75, v75, v75
	s_waitcnt lgkmcnt(0)
	v_cndmask_b32_e32 v81, v80, v83, vcc
	v_cndmask_b32_e32 v80, v85, v82, vcc
	v_cvt_pk_bf16_f32 v85, v76, v77
	v_pk_mul_f32 v[76:77], v[78:79], v[78:79]
	v_max_f32_e32 v74, 0, v74
	v_max_f32_e32 v75, 0, v75
	v_pk_mul_f32 v[72:73], v[72:73], v[72:73]
	v_cvt_pk_bf16_f32 v76, v76, v77
	v_cvt_pk_bf16_f32 v77, v72, v73
	v_pk_mul_f32 v[72:73], v[74:75], v[74:75]
	v_cndmask_b32_e32 v74, v85, v77, vcc
	v_cvt_pk_bf16_f32 v72, v72, v73
	v_cndmask_b32_e32 v73, v76, v72, vcc
	ds_bpermute_b32 v75, v132, v73
	ds_bpermute_b32 v74, v132, v74
	v_max_f32_e32 v68, v68, v68
	v_max_f32_e32 v69, v69, v69
	v_max_f32_e32 v68, 0, v68
	v_max_f32_e32 v69, 0, v69
	v_max_f32_e32 v70, v70, v70
	v_max_f32_e32 v71, v71, v71
	v_max_f32_e32 v64, v64, v64
	v_max_f32_e32 v65, v65, v65
	v_max_f32_e32 v70, 0, v70
	v_max_f32_e32 v71, 0, v71
	v_pk_mul_f32 v[68:69], v[68:69], v[68:69]
	v_max_f32_e32 v64, 0, v64
	v_max_f32_e32 v65, 0, v65
	v_max_f32_e32 v66, v66, v66
	v_max_f32_e32 v67, v67, v67
	s_waitcnt lgkmcnt(0)
	v_cndmask_b32_e32 v73, v72, v75, vcc
	v_cndmask_b32_e32 v72, v77, v74, vcc
	v_cvt_pk_bf16_f32 v77, v68, v69
	v_pk_mul_f32 v[68:69], v[70:71], v[70:71]
	v_max_f32_e32 v66, 0, v66
	v_max_f32_e32 v67, 0, v67
	v_pk_mul_f32 v[64:65], v[64:65], v[64:65]
	v_cvt_pk_bf16_f32 v68, v68, v69
	v_cvt_pk_bf16_f32 v69, v64, v65
	v_pk_mul_f32 v[64:65], v[66:67], v[66:67]
	v_max_f32_e32 v60, v60, v60
	v_cvt_pk_bf16_f32 v64, v64, v65
	v_cndmask_b32_e32 v65, v68, v64, vcc
	ds_bpermute_b32 v65, v132, v65
	v_max_f32_e32 v61, v61, v61
	v_max_f32_e32 v56, v56, v56
	v_max_f32_e32 v57, v57, v57
	v_max_f32_e32 v60, 0, v60
	v_max_f32_e32 v61, 0, v61
	v_max_f32_e32 v62, v62, v62
	v_max_f32_e32 v63, v63, v63
	v_max_f32_e32 v56, 0, v56
	v_max_f32_e32 v57, 0, v57
	v_max_f32_e32 v58, v58, v58
	v_max_f32_e32 v59, v59, v59
	v_max_f32_e32 v62, 0, v62
	v_max_f32_e32 v63, 0, v63
	v_pk_mul_f32 v[60:61], v[60:61], v[60:61]
	v_max_f32_e32 v58, 0, v58
	v_max_f32_e32 v59, 0, v59
	v_pk_mul_f32 v[56:57], v[56:57], v[56:57]
	s_waitcnt lgkmcnt(0)
	v_cndmask_b32_e32 v67, v64, v65, vcc
	v_cndmask_b32_e32 v65, v65, v68, vcc
	v_cvt_pk_bf16_f32 v68, v60, v61
	v_pk_mul_f32 v[60:61], v[62:63], v[62:63]
	v_cvt_pk_bf16_f32 v62, v56, v57
	v_pk_mul_f32 v[56:57], v[58:59], v[58:59]
	v_cvt_pk_bf16_f32 v61, v60, v61
	v_cvt_pk_bf16_f32 v56, v56, v57
	v_cndmask_b32_e32 v57, v61, v56, vcc
	v_cndmask_b32_e32 v58, v68, v62, vcc
	ds_bpermute_b32 v57, v132, v57
	ds_bpermute_b32 v63, v132, v58
	v_max_f32_e32 v52, v52, v52
	v_max_f32_e32 v53, v53, v53
	v_max_f32_e32 v48, v48, v48
	v_max_f32_e32 v49, v49, v49
	v_cndmask_b32_e32 v79, v83, v84, vcc
	v_cndmask_b32_e32 v78, v82, v93, vcc
	v_cndmask_b32_e32 v66, v77, v69, vcc
	v_add_u32_e32 v60, 0x80, v130
	v_max_f32_e32 v52, 0, v52
	v_max_f32_e32 v53, 0, v53
	v_max_f32_e32 v54, v54, v54
	v_max_f32_e32 v55, v55, v55
	v_max_f32_e32 v48, 0, v48
	v_max_f32_e32 v49, 0, v49
	v_max_f32_e32 v50, v50, v50
	v_max_f32_e32 v51, v51, v51
	global_store_dwordx4 v[108:109], v[78:81], off offset:256
	ds_bpermute_b32 v78, v132, v66
	s_waitcnt lgkmcnt(0)
	v_cndmask_b32_e32 v59, v56, v57, vcc
	v_cndmask_b32_e32 v57, v57, v61, vcc
	v_ashrrev_i32_e32 v61, 31, v60
	v_max_f32_e32 v54, 0, v54
	v_max_f32_e32 v55, 0, v55
	v_pk_mul_f32 v[52:53], v[52:53], v[52:53]
	v_max_f32_e32 v50, 0, v50
	v_max_f32_e32 v51, 0, v51
	v_pk_mul_f32 v[48:49], v[48:49], v[48:49]
	v_max_f32_e32 v44, v44, v44
	v_max_f32_e32 v45, v45, v45
	v_max_f32_e32 v40, v40, v40
	v_max_f32_e32 v41, v41, v41
	v_cndmask_b32_e32 v58, v62, v63, vcc
	v_cndmask_b32_e32 v56, v63, v68, vcc
	v_lshlrev_b64 v[60:61], 13, v[60:61]
	v_cvt_pk_bf16_f32 v62, v52, v53
	v_pk_mul_f32 v[52:53], v[54:55], v[54:55]
	v_cvt_pk_bf16_f32 v63, v48, v49
	v_pk_mul_f32 v[48:49], v[50:51], v[50:51]
	v_max_f32_e32 v44, 0, v44
	v_max_f32_e32 v45, 0, v45
	v_max_f32_e32 v46, v46, v46
	v_max_f32_e32 v47, v47, v47
	v_max_f32_e32 v40, 0, v40
	v_max_f32_e32 v41, 0, v41
	v_max_f32_e32 v42, v42, v42
	v_max_f32_e32 v43, v43, v43
	v_cvt_pk_bf16_f32 v55, v52, v53
	v_cvt_pk_bf16_f32 v48, v48, v49
	v_lshl_add_u64 v[52:53], v[120:121], 0, v[60:61]
	v_max_f32_e32 v46, 0, v46
	v_max_f32_e32 v47, 0, v47
	v_pk_mul_f32 v[44:45], v[44:45], v[44:45]
	v_max_f32_e32 v42, 0, v42
	v_max_f32_e32 v43, 0, v43
	v_pk_mul_f32 v[40:41], v[40:41], v[40:41]
	v_cndmask_b32_e32 v49, v55, v48, vcc
	global_store_dwordx4 v[52:53], v[56:59], off
	ds_bpermute_b32 v49, v132, v49
	v_cndmask_b32_e32 v66, v69, v78, vcc
	v_cvt_pk_bf16_f32 v56, v44, v45
	v_pk_mul_f32 v[44:45], v[46:47], v[46:47]
	v_cvt_pk_bf16_f32 v57, v40, v41
	v_pk_mul_f32 v[40:41], v[42:43], v[42:43]
	v_cvt_pk_bf16_f32 v47, v44, v45
	v_cvt_pk_bf16_f32 v40, v40, v41
	v_cndmask_b32_e32 v64, v78, v77, vcc
	v_cndmask_b32_e32 v50, v62, v63, vcc
	v_cndmask_b32_e32 v41, v47, v40, vcc
	global_store_dwordx4 v[90:91], v[64:67], off offset:256
	ds_bpermute_b32 v64, v132, v50
	ds_bpermute_b32 v41, v132, v41
	v_cndmask_b32_e32 v42, v56, v57, vcc
	v_add_u32_e32 v54, 0x90, v130
	ds_bpermute_b32 v58, v132, v42
	s_waitcnt lgkmcnt(0)
	v_cndmask_b32_e32 v51, v48, v49, vcc
	v_cndmask_b32_e32 v49, v49, v55, vcc
	v_ashrrev_i32_e32 v55, 31, v54
	v_max_f32_e32 v36, v36, v36
	v_max_f32_e32 v37, v37, v37
	v_max_f32_e32 v32, v32, v32
	v_max_f32_e32 v33, v33, v33
	v_lshlrev_b64 v[54:55], 13, v[54:55]
	v_add_u32_e32 v46, 0xa0, v130
	v_max_f32_e32 v36, 0, v36
	v_max_f32_e32 v37, 0, v37
	v_max_f32_e32 v38, v38, v38
	v_max_f32_e32 v39, v39, v39
	v_max_f32_e32 v32, 0, v32
	v_max_f32_e32 v33, 0, v33
	v_max_f32_e32 v34, v34, v34
	v_max_f32_e32 v35, v35, v35
	v_cndmask_b32_e32 v50, v63, v64, vcc
	v_cndmask_b32_e32 v48, v64, v62, vcc
	v_lshl_add_u64 v[44:45], v[120:121], 0, v[54:55]
	v_cndmask_b32_e32 v43, v40, v41, vcc
	v_cndmask_b32_e32 v41, v41, v47, vcc
	v_ashrrev_i32_e32 v47, 31, v46
	v_max_f32_e32 v38, 0, v38
	v_max_f32_e32 v39, 0, v39
	v_pk_mul_f32 v[36:37], v[36:37], v[36:37]
	v_max_f32_e32 v34, 0, v34
	v_max_f32_e32 v35, 0, v35
	v_pk_mul_f32 v[32:33], v[32:33], v[32:33]
	v_max_f32_e32 v28, v28, v28
	v_max_f32_e32 v29, v29, v29
	global_store_dwordx4 v[44:45], v[48:51], off
	v_lshlrev_b64 v[46:47], 13, v[46:47]
	v_max_f32_e32 v28, 0, v28
	v_cvt_pk_bf16_f32 v48, v36, v37
	v_pk_mul_f32 v[36:37], v[38:39], v[38:39]
	v_cvt_pk_bf16_f32 v49, v32, v33
	v_pk_mul_f32 v[32:33], v[34:35], v[34:35]
	v_max_f32_e32 v29, 0, v29
	v_max_f32_e32 v30, v30, v30
	v_max_f32_e32 v31, v31, v31
	v_max_f32_e32 v24, v24, v24
	v_max_f32_e32 v25, v25, v25
	v_cndmask_b32_e32 v42, v57, v58, vcc
	v_cndmask_b32_e32 v40, v58, v56, vcc
	v_cvt_pk_bf16_f32 v39, v36, v37
	v_cvt_pk_bf16_f32 v32, v32, v33
	v_lshl_add_u64 v[36:37], v[120:121], 0, v[46:47]
	v_max_f32_e32 v30, 0, v30
	v_max_f32_e32 v31, 0, v31
	v_pk_mul_f32 v[28:29], v[28:29], v[28:29]
	v_max_f32_e32 v24, 0, v24
	v_max_f32_e32 v25, 0, v25
	v_max_f32_e32 v26, v26, v26
	v_max_f32_e32 v27, v27, v27
	v_cndmask_b32_e32 v33, v39, v32, vcc
	global_store_dwordx4 v[36:37], v[40:43], off
	v_max_f32_e32 v26, 0, v26
	v_max_f32_e32 v27, 0, v27
	v_cvt_pk_bf16_f32 v40, v28, v29
	v_pk_mul_f32 v[28:29], v[30:31], v[30:31]
	v_pk_mul_f32 v[24:25], v[24:25], v[24:25]
	ds_bpermute_b32 v33, v132, v33
	v_cvt_pk_bf16_f32 v28, v28, v29
	v_cvt_pk_bf16_f32 v29, v24, v25
	v_pk_mul_f32 v[24:25], v[26:27], v[26:27]
	v_add_u32_e32 v38, 0xb0, v130
	v_cvt_pk_bf16_f32 v30, v24, v25
	v_cndmask_b32_e32 v25, v40, v29, vcc
	ds_bpermute_b32 v41, v132, v25
	v_max_f32_e32 v20, v20, v20
	v_max_f32_e32 v21, v21, v21
	s_waitcnt lgkmcnt(0)
	v_cndmask_b32_e32 v35, v32, v33, vcc
	v_cndmask_b32_e32 v33, v33, v39, vcc
	v_ashrrev_i32_e32 v39, 31, v38
	v_cndmask_b32_e32 v24, v28, v30, vcc
	v_max_f32_e32 v20, 0, v20
	v_max_f32_e32 v21, 0, v21
	v_max_f32_e32 v22, v22, v22
	v_max_f32_e32 v23, v23, v23
	v_max_f32_e32 v16, v16, v16
	v_max_f32_e32 v17, v17, v17
	ds_bpermute_b32 v31, v132, v24
	v_lshlrev_b64 v[24:25], 13, v[38:39]
	v_max_f32_e32 v22, 0, v22
	v_max_f32_e32 v23, 0, v23
	v_pk_mul_f32 v[20:21], v[20:21], v[20:21]
	v_max_f32_e32 v16, 0, v16
	v_max_f32_e32 v17, 0, v17
	v_max_f32_e32 v18, v18, v18
	v_max_f32_e32 v19, v19, v19
	v_lshl_add_u64 v[26:27], v[120:121], 0, v[24:25]
	v_cndmask_b32_e32 v24, v29, v41, vcc
	v_cvt_pk_bf16_f32 v29, v20, v21
	v_pk_mul_f32 v[20:21], v[22:23], v[22:23]
	v_max_f32_e32 v18, 0, v18
	v_max_f32_e32 v19, 0, v19
	v_pk_mul_f32 v[16:17], v[16:17], v[16:17]
	v_cvt_pk_bf16_f32 v20, v20, v21
	v_cvt_pk_bf16_f32 v21, v16, v17
	v_pk_mul_f32 v[16:17], v[18:19], v[18:19]
	v_cndmask_b32_e32 v18, v29, v21, vcc
	v_cvt_pk_bf16_f32 v16, v16, v17
	v_cndmask_b32_e32 v17, v20, v16, vcc
	ds_bpermute_b32 v19, v132, v17
	ds_bpermute_b32 v18, v132, v18
	v_max_f32_e32 v12, v12, v12
	v_max_f32_e32 v13, v13, v13
	v_max_f32_e32 v12, 0, v12
	v_max_f32_e32 v13, 0, v13
	v_max_f32_e32 v14, v14, v14
	v_max_f32_e32 v15, v15, v15
	v_max_f32_e32 v8, v8, v8
	v_max_f32_e32 v9, v9, v9
	v_max_f32_e32 v14, 0, v14
	v_max_f32_e32 v15, 0, v15
	v_pk_mul_f32 v[12:13], v[12:13], v[12:13]
	v_max_f32_e32 v8, 0, v8
	v_max_f32_e32 v9, 0, v9
	v_max_f32_e32 v10, v10, v10
	v_max_f32_e32 v11, v11, v11
	s_waitcnt lgkmcnt(0)
	v_cndmask_b32_e32 v17, v16, v19, vcc
	v_cndmask_b32_e32 v16, v21, v18, vcc
	v_cvt_pk_bf16_f32 v21, v12, v13
	v_pk_mul_f32 v[12:13], v[14:15], v[14:15]
	v_max_f32_e32 v10, 0, v10
	v_max_f32_e32 v11, 0, v11
	v_pk_mul_f32 v[8:9], v[8:9], v[8:9]
	v_cvt_pk_bf16_f32 v12, v12, v13
	v_cvt_pk_bf16_f32 v13, v8, v9
	v_pk_mul_f32 v[8:9], v[10:11], v[10:11]
	v_cndmask_b32_e32 v10, v21, v13, vcc
	v_cvt_pk_bf16_f32 v8, v8, v9
	v_cndmask_b32_e32 v9, v12, v8, vcc
	ds_bpermute_b32 v11, v132, v9
	ds_bpermute_b32 v10, v132, v10
	v_max_f32_e32 v4, v4, v4
	v_max_f32_e32 v5, v5, v5
	v_max_f32_e32 v4, 0, v4
	v_max_f32_e32 v5, 0, v5
	v_max_f32_e32 v6, v6, v6
	v_max_f32_e32 v7, v7, v7
	v_max_f32_e32 v0, v0, v0
	v_max_f32_e32 v1, v1, v1
	v_max_f32_e32 v6, 0, v6
	v_max_f32_e32 v7, 0, v7
	v_pk_mul_f32 v[4:5], v[4:5], v[4:5]
	v_max_f32_e32 v0, 0, v0
	v_max_f32_e32 v1, 0, v1
	v_max_f32_e32 v2, v2, v2
	v_max_f32_e32 v3, v3, v3
	s_waitcnt lgkmcnt(0)
	v_cndmask_b32_e32 v9, v8, v11, vcc
	v_cndmask_b32_e32 v8, v13, v10, vcc
	v_cvt_pk_bf16_f32 v13, v4, v5
	v_pk_mul_f32 v[4:5], v[6:7], v[6:7]
	v_max_f32_e32 v2, 0, v2
	v_max_f32_e32 v3, 0, v3
	v_pk_mul_f32 v[0:1], v[0:1], v[0:1]
	v_cvt_pk_bf16_f32 v4, v4, v5
	v_cvt_pk_bf16_f32 v5, v0, v1
	v_pk_mul_f32 v[0:1], v[2:3], v[2:3]
	v_cndmask_b32_e32 v98, v112, v113, vcc
	v_cvt_pk_bf16_f32 v0, v0, v1
	v_cndmask_b32_e32 v34, v48, v49, vcc
	v_cndmask_b32_e32 v15, v19, v20, vcc
	v_cndmask_b32_e32 v14, v18, v29, vcc
	v_cndmask_b32_e32 v1, v4, v0, vcc
	v_cndmask_b32_e32 v2, v13, v5, vcc
	ds_bpermute_b32 v114, v132, v98
	ds_bpermute_b32 v50, v132, v34
	global_store_dwordx4 v[44:45], v[14:17], off offset:256
	ds_bpermute_b32 v1, v132, v1
	ds_bpermute_b32 v14, v132, v2
	s_lshr_b32 s2, s90, 3
	s_waitcnt lgkmcnt(0)
	v_cndmask_b32_e32 v98, v113, v114, vcc
	v_cndmask_b32_e32 v96, v114, v112, vcc
	v_cndmask_b32_e32 v89, v94, v95, vcc
	v_cndmask_b32_e32 v87, v95, v92, vcc
	v_cndmask_b32_e32 v86, v105, v104, vcc
	v_cndmask_b32_e32 v71, v75, v76, vcc
	v_cndmask_b32_e32 v70, v74, v85, vcc
	v_cndmask_b32_e32 v34, v49, v50, vcc
	v_cndmask_b32_e32 v32, v50, v48, vcc
	v_cndmask_b32_e32 v25, v30, v31, vcc
	v_cndmask_b32_e32 v23, v31, v28, vcc
	v_cndmask_b32_e32 v22, v41, v40, vcc
	v_cndmask_b32_e32 v7, v11, v12, vcc
	v_cndmask_b32_e32 v6, v10, v21, vcc
	v_cndmask_b32_e32 v3, v0, v1, vcc
	v_cndmask_b32_e32 v2, v5, v14, vcc
	v_cndmask_b32_e32 v1, v1, v4, vcc
	v_cndmask_b32_e32 v0, v14, v13, vcc
	s_andn2_b64 vcc, exec, s[38:39]
	s_add_i32 s0, s0, s2
	global_store_dwordx4 v[90:91], v[96:99], off
	global_store_dwordx4 v[116:117], v[86:89], off offset:256
	global_store_dwordx4 v[100:101], v[70:73], off offset:256
	global_store_dwordx4 v[26:27], v[32:35], off
	global_store_dwordx4 v[52:53], v[22:25], off offset:256
	global_store_dwordx4 v[36:37], v[6:9], off offset:256
	global_store_dwordx4 v[26:27], v[0:3], off offset:256
	s_waitcnt vmcnt(16)
	s_barrier
	s_cbranch_vccz .LBB0_2921

.LBB0_2913:
	s_andn2_b64 vcc, exec, s[44:45]
	s_cbranch_vccnz .LBB0_2915
.LBB0_2914:
	s_waitcnt vmcnt(0)
.LBB0_2915:
	v_add_u32_e32 v2, v0, v2
	v_and_b32_e32 v2, 0xfffffc00, v2
	v_sub_u32_e32 v2, v0, v2
	v_lshrrev_b32_e32 v5, 4, v2
	v_add_u32_e32 v3, v128, v3
	v_bitop3_b32 v5, v5, v2, 32 bitop3:0x6c
	v_ashrrev_i32_e32 v2, 31, v2
	v_ashrrev_i32_e32 v3, 6, v3
	v_lshrrev_b32_e32 v2, 26, v2
	v_lshlrev_b32_e32 v6, 3, v3
	v_add_u32_e32 v2, v5, v2
	s_and_b32 s2, s0, 3
	v_and_b32_e32 v6, -16, v6
	v_ashrrev_i32_e32 v7, 6, v2
	s_lshl_b32 s2, s2, 18
	v_add_u32_e32 v2, v7, v6
	v_mul_i32_i24_e32 v6, 64, v7
	s_add_i32 s2, s48, s2
	v_lshlrev_b32_e32 v3, 5, v3
	v_sub_u32_e32 v5, v5, v6
	s_lshl_b32 s2, s2, 1
	s_lshl_b32 s4, s61, 19
	v_and_b32_e32 v3, 32, v3
	v_ashrrev_i16_sdwa v5, v150, sext(v5) dst_sel:DWORD dst_unused:UNUSED_PAD src0_sel:DWORD src1_sel:BYTE_0
	s_add_u32 s4, s40, s4
	v_add_u32_sdwa v138, v3, sext(v5) dst_sel:DWORD dst_unused:UNUSED_PAD src0_sel:DWORD src1_sel:WORD_0
	v_ashrrev_i32_e32 v3, 31, v2
	s_addc_u32 s5, s46, 0
	v_lshlrev_b64 v[130:131], 11, v[2:3]
	v_ashrrev_i32_e32 v139, 31, v138
	v_lshl_add_u64 v[2:3], s[4:5], 0, v[130:131]
	v_lshlrev_b64 v[132:133], 1, v[138:139]
	v_add_u32_e32 v167, s50, v0
	v_lshl_add_u64 v[2:3], v[2:3], 0, v[132:133]
	v_readfirstlane_b32 s37, v167
	v_lshl_add_u64 v[2:3], v[2:3], 0, s[10:11]
	s_mov_b32 m0, s37
	s_barrier
	global_load_lds_dwordx4 v[2:3], off
	v_ashrrev_i32_e32 v2, 31, v1
	v_lshrrev_b32_e32 v2, 22, v2
	v_add_u32_e32 v2, v1, v2
	v_ashrrev_i32_e32 v3, 10, v2
	v_mul_i32_i24_e32 v2, 0x400, v3
	v_sub_u32_e32 v2, v1, v2
	v_lshrrev_b32_e32 v5, 4, v2
	v_bitop3_b32 v5, v5, v2, 32 bitop3:0x6c
	v_ashrrev_i32_e32 v6, 31, v5
	v_lshrrev_b32_e32 v6, 26, v6
	v_add_u32_e32 v6, v5, v6
	v_ashrrev_i32_e32 v7, 6, v6
	v_and_b32_e32 v6, 0xc0, v6
	v_lshlrev_b32_e32 v2, 3, v3
	v_lshlrev_b32_e32 v3, 5, v3
	v_sub_u32_e32 v5, v5, v6
	v_and_b32_e32 v2, -16, v2
	v_and_b32_e32 v3, 32, v3
	v_ashrrev_i16_sdwa v5, v150, sext(v5) dst_sel:DWORD dst_unused:UNUSED_PAD src0_sel:DWORD src1_sel:BYTE_0
	v_add_u32_e32 v2, v7, v2
	v_add_u32_sdwa v140, v3, sext(v5) dst_sel:DWORD dst_unused:UNUSED_PAD src0_sel:DWORD src1_sel:WORD_0
	v_add_u32_e32 v5, s50, v1
	v_ashrrev_i32_e32 v3, 31, v2
	v_readfirstlane_b32 s37, v5
	v_lshlrev_b64 v[134:135], 11, v[2:3]
	v_ashrrev_i32_e32 v141, 31, v140
	s_mov_b32 m0, s37
	s_ashr_i32 s37, s36, 31
	v_lshl_add_u64 v[2:3], s[4:5], 0, v[134:135]
	v_lshlrev_b64 v[136:137], 1, v[140:141]
	s_lshl_b64 s[38:39], s[36:37], 11
	v_lshl_add_u64 v[2:3], v[2:3], 0, v[136:137]
	s_add_u32 s42, s1, s38
	v_lshl_add_u64 v[2:3], v[2:3], 0, s[10:11]
	s_addc_u32 s43, s23, s39
	global_load_lds_dwordx4 v[2:3], off
	v_lshl_add_u64 v[2:3], s[42:43], 0, v[130:131]
	v_add_u32_e32 v169, 0x8000, v152
	v_lshl_add_u64 v[2:3], v[2:3], 0, v[132:133]
	v_readfirstlane_b32 s37, v169
	v_lshl_add_u64 v[2:3], v[2:3], 0, s[10:11]
	s_mov_b32 m0, s37
	v_add_u32_e32 v170, 0xa000, v152
	global_load_lds_dwordx4 v[2:3], off
	v_lshl_add_u64 v[2:3], s[42:43], 0, v[134:135]
	v_lshl_add_u64 v[2:3], v[2:3], 0, v[136:137]
	v_readfirstlane_b32 s37, v170
	s_add_u32 s4, s4, 0x40080
	v_lshl_add_u64 v[2:3], v[2:3], 0, s[10:11]
	s_mov_b32 m0, s37
	s_addc_u32 s5, s5, 0
	v_add_u32_e32 v171, s51, v0
	global_load_lds_dwordx4 v[2:3], off
	v_lshl_add_u64 v[2:3], s[4:5], 0, v[130:131]
	v_readfirstlane_b32 s37, v171
	v_lshl_add_u64 v[2:3], v[2:3], 0, v[132:133]
	s_mov_b32 m0, s37
	v_add_u32_e32 v0, s51, v1
	global_load_lds_dwordx4 v[2:3], off
	v_lshl_add_u64 v[2:3], s[4:5], 0, v[134:135]
	v_readfirstlane_b32 s4, v0
	v_lshl_add_u64 v[2:3], v[2:3], 0, v[136:137]
	s_mov_b32 m0, s4
	v_and_b32_e32 v156, 15, v128
	global_load_lds_dwordx4 v[2:3], off
	v_bfe_u32 v155, v128, 4, 2
	v_lshlrev_b32_e32 v2, 2, v128
	v_lshlrev_b32_e32 v0, 4, v155
	v_lshlrev_b32_e32 v1, 6, v156
	v_and_b32_e32 v2, 32, v2
	v_bitop3_b32 v1, v0, v2, v1 bitop3:0x36
	v_add_u32_e32 v6, s47, v1
	v_add_u32_e32 v7, s49, v1
	v_add_u32_e32 v8, s50, v1
	v_add_u32_e32 v9, s51, v1
	v_add_u32_e32 v10, 0, v1
	v_lshlrev_b32_e32 v1, 6, v128
	v_and_or_b32 v0, v1, s58, v0
	v_bfe_u32 v154, v128, 6, 2
	s_waitcnt vmcnt(22)
	v_lshlrev_b32_e32 v157, 6, v4
	v_lshlrev_b32_e32 v4, 13, v4
	v_xad_u32 v11, v0, v2, 0
	v_lshl_add_u64 v[0:1], v[130:131], 0, v[132:133]
	v_lshlrev_b32_e32 v5, 12, v154
	v_or_b32_e32 v12, 0x800, v4
	v_or_b32_e32 v13, 0x1000, v4
	v_or_b32_e32 v14, 0x1800, v4
	v_lshl_add_u64 v[142:143], v[0:1], 0, s[2:3]
	v_lshl_add_u64 v[2:3], v[134:135], 0, v[136:137]
	v_lshl_add_u64 v[146:147], v[0:1], 0, s[38:39]
	v_mov_b32_e32 v0, 0
	v_lshl_add_u64 v[144:145], v[2:3], 0, s[2:3]
	v_lshl_add_u64 v[148:149], v[2:3], 0, s[38:39]
	s_mov_b32 s2, -2
	v_add_u32_e32 v172, v6, v5
	v_add_u32_e32 v161, v10, v4
	v_add_u32_e32 v160, v11, v12
	v_add_u32_e32 v159, v11, v13
	v_add_u32_e32 v158, v11, v14
	v_add_u32_e32 v168, v7, v5
	v_add_u32_e32 v163, v8, v5
	v_add_u32_e32 v162, v9, v5
	v_mov_b32_e32 v1, v0
	v_mov_b32_e32 v2, v0
	v_mov_b32_e32 v3, v0
	v_mov_b32_e32 v4, v0
	v_mov_b32_e32 v5, v0
	v_mov_b32_e32 v6, v0
	v_mov_b32_e32 v7, v0
	v_mov_b32_e32 v8, v0
	v_mov_b32_e32 v9, v0
	v_mov_b32_e32 v10, v0
	v_mov_b32_e32 v11, v0
	v_mov_b32_e32 v12, v0
	v_mov_b32_e32 v13, v0
	v_mov_b32_e32 v14, v0
	v_mov_b32_e32 v15, v0
	v_mov_b32_e32 v16, v0
	v_mov_b32_e32 v17, v0
	v_mov_b32_e32 v18, v0
	v_mov_b32_e32 v19, v0
	v_mov_b32_e32 v20, v0
	v_mov_b32_e32 v21, v0
	v_mov_b32_e32 v22, v0
	v_mov_b32_e32 v23, v0
	v_mov_b32_e32 v24, v0
	v_mov_b32_e32 v25, v0
	v_mov_b32_e32 v26, v0
	v_mov_b32_e32 v27, v0
	v_mov_b32_e32 v28, v0
	v_mov_b32_e32 v29, v0
	v_mov_b32_e32 v30, v0
	v_mov_b32_e32 v31, v0
	v_mov_b32_e32 v32, v0
	v_mov_b32_e32 v33, v0
	v_mov_b32_e32 v34, v0
	v_mov_b32_e32 v35, v0
	v_mov_b32_e32 v36, v0
	v_mov_b32_e32 v37, v0
	v_mov_b32_e32 v38, v0
	v_mov_b32_e32 v39, v0
	v_mov_b32_e32 v40, v0
	v_mov_b32_e32 v41, v0
	v_mov_b32_e32 v42, v0
	v_mov_b32_e32 v43, v0
	v_mov_b32_e32 v44, v0
	v_mov_b32_e32 v45, v0
	v_mov_b32_e32 v46, v0
	v_mov_b32_e32 v47, v0
	v_mov_b32_e32 v48, v0
	v_mov_b32_e32 v49, v0
	v_mov_b32_e32 v50, v0
	v_mov_b32_e32 v51, v0
	v_mov_b32_e32 v52, v0
	v_mov_b32_e32 v53, v0
	v_mov_b32_e32 v54, v0
	v_mov_b32_e32 v55, v0
	v_mov_b32_e32 v56, v0
	v_mov_b32_e32 v57, v0
	v_mov_b32_e32 v58, v0
	v_mov_b32_e32 v59, v0
	v_mov_b32_e32 v60, v0
	v_mov_b32_e32 v61, v0
	v_mov_b32_e32 v62, v0
	v_mov_b32_e32 v63, v0
	v_mov_b32_e32 v64, v0
	v_mov_b32_e32 v65, v0
	v_mov_b32_e32 v66, v0
	v_mov_b32_e32 v67, v0
	v_mov_b32_e32 v68, v0
	v_mov_b32_e32 v69, v0
	v_mov_b32_e32 v70, v0
	v_mov_b32_e32 v71, v0
	v_mov_b32_e32 v72, v0
	v_mov_b32_e32 v73, v0
	v_mov_b32_e32 v74, v0
	v_mov_b32_e32 v75, v0
	v_mov_b32_e32 v76, v0
	v_mov_b32_e32 v77, v0
	v_mov_b32_e32 v78, v0
	v_mov_b32_e32 v79, v0
	v_mov_b32_e32 v80, v0
	v_mov_b32_e32 v81, v0
	v_mov_b32_e32 v82, v0
	v_mov_b32_e32 v83, v0
	v_mov_b32_e32 v84, v0
	v_mov_b32_e32 v85, v0
	v_mov_b32_e32 v86, v0
	v_mov_b32_e32 v87, v0
	v_mov_b32_e32 v88, v0
	v_mov_b32_e32 v89, v0
	v_mov_b32_e32 v90, v0
	v_mov_b32_e32 v91, v0
	v_mov_b32_e32 v92, v0
	v_mov_b32_e32 v93, v0
	v_mov_b32_e32 v94, v0
	v_mov_b32_e32 v95, v0
	v_mov_b32_e32 v96, v0
	v_mov_b32_e32 v97, v0
	v_mov_b32_e32 v98, v0
	v_mov_b32_e32 v99, v0
	v_mov_b32_e32 v100, v0
	v_mov_b32_e32 v101, v0
	v_mov_b32_e32 v102, v0
	v_mov_b32_e32 v103, v0
	v_mov_b32_e32 v104, v0
	v_mov_b32_e32 v105, v0
	v_mov_b32_e32 v106, v0
	v_mov_b32_e32 v107, v0
	v_mov_b32_e32 v108, v0
	v_mov_b32_e32 v109, v0
	v_mov_b32_e32 v110, v0
	v_mov_b32_e32 v111, v0
	v_mov_b32_e32 v112, v0
	v_mov_b32_e32 v113, v0
	v_mov_b32_e32 v114, v0
	v_mov_b32_e32 v115, v0
	v_mov_b32_e32 v116, v0
	v_mov_b32_e32 v117, v0
	v_mov_b32_e32 v118, v0
	v_mov_b32_e32 v119, v0
	v_mov_b32_e32 v120, v0
	v_mov_b32_e32 v121, v0
	v_mov_b32_e32 v122, v0
	v_mov_b32_e32 v123, v0
	v_mov_b32_e32 v124, v0
	v_mov_b32_e32 v125, v0
	v_mov_b32_e32 v126, v0
	v_mov_b32_e32 v127, v0
	s_barrier
